# prep balance step 2: workgroups 0..63 skip weight-conversion iterations 2 and 3; pooled in-projection fold of layer 3 moved to workgroups 128..255
# speedup vs baseline: 1.0295x; 1.0066x over previous
.LBB0_20:
	v_readlane_b32 s0, v254, 1
	v_readlane_b32 s33, v254, 0
	v_readlane_b32 s1, v254, 2
	s_load_dword s0, s[0:1], 0x10
	v_readlane_b32 s36, v254, 19
	s_mul_i32 s2, s8, 0x3000
	v_readlane_b32 s38, v254, 21
	v_readlane_b32 s39, v254, 22
	s_waitcnt lgkmcnt(0)
	s_lshr_b32 s0, s0, 16
	s_cmp_lg_u32 s0, 0
	s_cselect_b64 s[0:1], -1, 0
	s_cmp_lg_u64 s[0:1], 0
	s_addc_u32 s18, s69, 0
	s_lshl_b32 s26, s8, 1
	s_add_u32 s70, s38, s2
	s_addc_u32 s71, s39, 0
	s_mul_i32 s0, s8, 0x2100000
	v_readlane_b32 s2, v254, 40
	s_mul_hi_u32 s1, s26, 0x1080000
	v_readlane_b32 s3, v254, 41
	s_add_u32 s0, s2, s0
	s_addc_u32 s1, s3, s1
	s_mov_b32 s27, s18
	s_cmp_eq_u32 s18, 0x100
	s_cbranch_scc0 .Lw_norm
	s_cmp_ge_u32 s8, 2
	s_cbranch_scc0 .Lw_norm
	s_cmp_lt_u32 s33, 64
	s_cbranch_scc1 .LBB0_19
	s_sub_i32 s33, s33, 64
	s_movk_i32 s27, 0xc0

.LBB0_313:
	s_cmp_eq_u32 s18, 0x100
	s_cbranch_scc0 .Lpf_norm
	s_cmp_eq_u32 s8, 3
	s_cbranch_scc0 .Lpf_norm
	s_sub_i32 s33, s33, 64
	s_cmp_lt_u32 s33, 0x80
	s_cselect_b32 s33, s33, 0x7000
	s_cmpk_lt_i32 s33, 0x80
	s_cselect_b64 s[2:3], -1, 0

.LBB0_401:
	s_or_b32 s26, s26, 1
	s_add_u32 s24, s70, 0x2000
	s_addc_u32 s25, s71, 0
	s_mul_i32 s0, s26, 0x1080000
	v_readlane_b32 s2, v254, 40
	s_mul_hi_u32 s1, s26, 0x1080000
	v_readlane_b32 s3, v254, 41
	s_add_u32 s0, s2, s0
	v_readlane_b32 s12, v254, 0
	s_addc_u32 s1, s3, s1
	s_mov_b32 s13, s18
	s_cmp_eq_u32 s18, 0x100
	s_cbranch_scc0 .Lw_norm2
	s_cmp_ge_u32 s8, 2
	s_cbranch_scc0 .Lw_norm2
	s_sub_i32 s12, s12, 64
	s_movk_i32 s13, 0xc0
